# bf16 rounding peephole also applied to the LayerNorm phase and the phase-0 conversion code (72 more packed pairs)
# speedup vs baseline: 1.0044x; 1.0015x over previous
; DI unsigned pk2(float lo, float hi) { return f2bf(lo) | (f2bf(hi) << 16); }
; DI void conv_T(const float* src, int K, int N, bf16_t* dst, int grp, int gstride, int goff, LAS float* tile) {
;     ...
;         {
;             const int nn = tid >> 3, k8 = (tid & 7) * 8, n = n0 + nn;
;             if (n < N) {
;                 float x[8];
; #pragma unroll
;                 for (int j = 0; j < 8; ++j) x[j] = tile[(k8 + j) * 65 + nn];
;                 u32x4 w; w.x = pk2(x[0], x[1]); w.y = pk2(x[2], x[3]); w.z = pk2(x[4], x[5]); w.w = pk2(x[6], x[7]);
;                 const size_t row = (size_t)(n / grp) * gstride + (n % grp) + goff;
;                 *(u32x4*)(dst + row * K + k0 + k8) = w;
;             }
.LBB0_56:
	s_mul_hi_i32 s12, s26, 0x2e8ba2e9
	s_lshr_b32 s13, s12, 31
	s_ashr_i32 s26, s12, 3
	s_add_i32 s26, s26, s13
	s_waitcnt lgkmcnt(0)
	s_barrier
	s_mul_i32 s12, s26, 0xfffff500
	v_add_u32_e32 v8, s18, v11
	v_add_u32_e32 v9, s12, v8
	v_cmp_gt_i32_e32 vcc, s51, v9
	s_and_saveexec_b64 s[12:13], vcc
	s_cbranch_execz .LBB0_49
	ds_read2_b32 v[18:19], v16 offset1:65
	ds_read2_b32 v[20:21], v16 offset0:130 offset1:195
	v_add_u32_e32 v17, 0x400, v16
	ds_read2_b32 v[22:23], v17 offset0:4 offset1:69
	ds_read2_b32 v[24:25], v17 offset0:134 offset1:199
	s_lshl_b32 s40, s26, 6
	s_waitcnt lgkmcnt(3)
	v_cvt_pk_bf16_f32 v18, v18, v19
	s_waitcnt lgkmcnt(2)
	v_cvt_pk_bf16_f32 v19, v20, v21
	s_waitcnt lgkmcnt(1)
	v_cvt_pk_bf16_f32 v20, v22, v23
	s_waitcnt lgkmcnt(0)
	v_cvt_pk_bf16_f32 v21, v24, v25
	v_ashrrev_i32_e32 v17, 31, v9
	v_lshrrev_b32_e32 v17, 25, v17
	v_add_u32_e32 v9, v9, v17
	v_ashrrev_i32_e32 v22, 7, v9
	v_and_b32_e32 v9, 0xffffff80, v9
	s_mulk_i32 s26, 0xb00
	v_add_u32_e32 v9, s26, v9
	v_ashrrev_i32_e32 v23, 31, v22
	v_sub_u32_e32 v8, v8, v9
	v_ashrrev_i32_e32 v9, 31, v8
	v_lshlrev_b64 v[22:23], 19, v[22:23]
	v_lshl_add_u64 v[22:23], s[6:7], 0, v[22:23]
	v_lshlrev_b64 v[8:9], 11, v[8:9]
	v_lshl_add_u64 v[8:9], v[22:23], 0, v[8:9]
	s_ashr_i32 s41, s40, 31
	v_lshl_add_u64 v[8:9], s[40:41], 1, v[8:9]
	v_lshl_add_u64 v[8:9], v[8:9], 0, v[136:137]
	global_store_dwordx4 v[8:9], v[18:21], off
	s_branch .LBB0_49

; DI unsigned pk2(float lo, float hi) { return f2bf(lo) | (f2bf(hi) << 16); }
; DI void conv_T(const float* src, int K, int N, bf16_t* dst, int grp, int gstride, int goff, LAS float* tile) {
;     ...
;         {
;             const int nn = tid >> 3, k8 = (tid & 7) * 8, n = n0 + nn;
;             if (n < N) {
;                 float x[8];
; #pragma unroll
;                 for (int j = 0; j < 8; ++j) x[j] = tile[(k8 + j) * 65 + nn];
;                 u32x4 w; w.x = pk2(x[0], x[1]); w.y = pk2(x[2], x[3]); w.z = pk2(x[4], x[5]); w.w = pk2(x[6], x[7]);
;                 const size_t row = (size_t)(n / grp) * gstride + (n % grp) + goff;
;                 *(u32x4*)(dst + row * K + k0 + k8) = w;
;             }
.LBB0_71:
	s_mul_hi_i32 s12, s26, 0x2e8ba2e9
	s_lshr_b32 s13, s12, 31
	s_ashr_i32 s26, s12, 3
	s_add_i32 s26, s26, s13
	s_waitcnt lgkmcnt(0)
	s_barrier
	s_mul_i32 s12, s26, 0xfffff500
	v_add_u32_e32 v9, s18, v13
	v_add_u32_e32 v10, s12, v9
	v_cmp_gt_i32_e32 vcc, s51, v10
	s_and_saveexec_b64 s[12:13], vcc
	s_cbranch_execz .LBB0_64
	ds_read2_b32 v[18:19], v16 offset1:65
	ds_read2_b32 v[20:21], v16 offset0:130 offset1:195
	v_add_u32_e32 v11, 0x400, v16
	ds_read2_b32 v[22:23], v11 offset0:4 offset1:69
	ds_read2_b32 v[24:25], v11 offset0:134 offset1:199
	s_lshl_b32 s40, s26, 6
	s_waitcnt lgkmcnt(3)
	v_cvt_pk_bf16_f32 v18, v18, v19
	s_waitcnt lgkmcnt(2)
	v_cvt_pk_bf16_f32 v19, v20, v21
	s_waitcnt lgkmcnt(1)
	v_cvt_pk_bf16_f32 v20, v22, v23
	s_waitcnt lgkmcnt(0)
	v_cvt_pk_bf16_f32 v21, v24, v25
	v_ashrrev_i32_e32 v11, 31, v10
	v_lshrrev_b32_e32 v11, 25, v11
	v_add_u32_e32 v17, v10, v11
	v_ashrrev_i32_e32 v10, 7, v17
	v_and_b32_e32 v17, 0xffffff80, v17
	s_mulk_i32 s26, 0xb00
	v_add_u32_e32 v17, s26, v17
	v_ashrrev_i32_e32 v11, 31, v10
	v_sub_u32_e32 v9, v9, v17
	v_add_u32_e32 v136, 0x80, v9
	v_lshlrev_b64 v[10:11], 19, v[10:11]
	v_lshl_add_u64 v[10:11], s[6:7], 0, v[10:11]
	v_lshlrev_b64 v[22:23], 11, v[136:137]
	v_lshl_add_u64 v[10:11], v[10:11], 0, v[22:23]
	s_ashr_i32 s41, s40, 31
	v_lshl_add_u64 v[10:11], s[40:41], 1, v[10:11]
	v_mov_b32_e32 v9, v137
	v_lshl_add_u64 v[10:11], v[10:11], 0, v[8:9]
	global_store_dwordx4 v[10:11], v[18:21], off
	s_branch .LBB0_64

; DI unsigned pk2(float lo, float hi) { return f2bf(lo) | (f2bf(hi) << 16); }
; DI void conv_T(const float* src, int K, int N, bf16_t* dst, int grp, int gstride, int goff, LAS float* tile) {
;     ...
;         {
;             const int nn = tid >> 3, k8 = (tid & 7) * 8, n = n0 + nn;
;             if (n < N) {
;                 float x[8];
; #pragma unroll
;                 for (int j = 0; j < 8; ++j) x[j] = tile[(k8 + j) * 65 + nn];
;                 u32x4 w; w.x = pk2(x[0], x[1]); w.y = pk2(x[2], x[3]); w.z = pk2(x[4], x[5]); w.w = pk2(x[6], x[7]);
;                 const size_t row = (size_t)(n / grp) * gstride + (n % grp) + goff;
;                 *(u32x4*)(dst + row * K + k0 + k8) = w;
;             }
.LBB0_86:
	s_ashr_i32 s10, s18, 31
	s_lshr_b32 s10, s10, 28
	s_add_i32 s10, s18, s10
	s_ashr_i32 s18, s10, 4
	s_waitcnt lgkmcnt(0)
	s_barrier
	v_add_u32_e32 v8, s16, v13
	s_lshl_b32 s10, s18, 10
	v_subrev_u32_e32 v8, s10, v8
	v_cmp_gt_i32_e32 vcc, s31, v8
	s_and_saveexec_b64 s[10:11], vcc
	s_cbranch_execz .LBB0_79
	ds_read2_b32 v[10:11], v16 offset1:65
	ds_read2_b32 v[20:21], v16 offset0:130 offset1:195
	v_add_u32_e32 v9, 0x400, v16
	ds_read2_b32 v[22:23], v9 offset0:4 offset1:69
	ds_read2_b32 v[24:25], v9 offset0:134 offset1:199
	s_lshl_b32 s18, s18, 6
	s_waitcnt lgkmcnt(3)
	v_cvt_pk_bf16_f32 v18, v10, v11
	s_waitcnt lgkmcnt(2)
	v_cvt_pk_bf16_f32 v19, v20, v21
	s_waitcnt lgkmcnt(1)
	v_cvt_pk_bf16_f32 v20, v22, v23
	s_waitcnt lgkmcnt(0)
	v_cvt_pk_bf16_f32 v21, v24, v25
	v_ashrrev_i32_e32 v9, 31, v8
	v_lshrrev_b32_e32 v9, 2, v9
	v_add_u32_e32 v9, v8, v9
	v_and_b32_e32 v9, -2.0, v9
	v_sub_u32_e32 v10, v8, v9
	v_mov_b64_e32 v[8:9], s[6:7]
	v_mad_i64_i32 v[8:9], s[40:41], v10, s30, v[8:9]
	s_ashr_i32 s19, s18, 31
	v_lshl_add_u64 v[8:9], s[18:19], 1, v[8:9]
	v_lshl_add_u64 v[8:9], v[8:9], 0, v[136:137]
	global_store_dwordx4 v[8:9], v[18:21], off
	s_branch .LBB0_79

; DI unsigned pk2(float lo, float hi) { return f2bf(lo) | (f2bf(hi) << 16); }
; DI void conv_T(const float* src, int K, int N, bf16_t* dst, int grp, int gstride, int goff, LAS float* tile) {
;     ...
;         {
;             const int nn = tid >> 3, k8 = (tid & 7) * 8, n = n0 + nn;
;             if (n < N) {
;                 float x[8];
; #pragma unroll
;                 for (int j = 0; j < 8; ++j) x[j] = tile[(k8 + j) * 65 + nn];
;                 u32x4 w; w.x = pk2(x[0], x[1]); w.y = pk2(x[2], x[3]); w.z = pk2(x[4], x[5]); w.w = pk2(x[6], x[7]);
;                 const size_t row = (size_t)(n / grp) * gstride + (n % grp) + goff;
;                 *(u32x4*)(dst + row * K + k0 + k8) = w;
;             }
.LBB0_101:
	s_ashr_i32 s2, s8, 31
	s_lshr_b32 s2, s2, 28
	s_add_i32 s2, s8, s2
	s_ashr_i32 s8, s2, 4
	s_waitcnt lgkmcnt(0)
	s_barrier
	v_add_u32_e32 v8, s6, v13
	s_lshl_b32 s2, s8, 10
	v_subrev_u32_e32 v8, s2, v8
	v_cmp_gt_i32_e32 vcc, s31, v8
	s_and_saveexec_b64 s[2:3], vcc
	s_cbranch_execz .LBB0_94
	ds_read2_b32 v[10:11], v16 offset1:65
	ds_read2_b32 v[20:21], v16 offset0:130 offset1:195
	v_add_u32_e32 v9, 0x400, v16
	ds_read2_b32 v[22:23], v9 offset0:4 offset1:69
	ds_read2_b32 v[24:25], v9 offset0:134 offset1:199
	v_readlane_b32 s10, v253, 26
	s_waitcnt lgkmcnt(3)
	s_nop 0
	s_nop 0
	s_nop 0
	v_cvt_pk_bf16_f32 v18, v10, v11
	s_waitcnt lgkmcnt(2)
	v_cvt_pk_bf16_f32 v19, v20, v21
	s_waitcnt lgkmcnt(1)
	v_cvt_pk_bf16_f32 v20, v22, v23
	s_waitcnt lgkmcnt(0)
	v_cvt_pk_bf16_f32 v9, v24, v24
	v_lshrrev_b32_e32 v9, 16, v9
	v_cvt_pk_bf16_f32 v10, v25, v25
	v_and_or_b32 v21, v10, s39, v9
	v_ashrrev_i32_e32 v9, 31, v8
	v_lshrrev_b32_e32 v9, 2, v9
	v_add_u32_e32 v9, v8, v9
	v_and_b32_e32 v9, -2.0, v9
	v_sub_u32_e32 v8, v8, v9
	v_ashrrev_i32_e32 v9, 31, v8
	s_lshl_b32 s8, s8, 6
	v_lshlrev_b64 v[8:9], 11, v[8:9]
	v_readlane_b32 s11, v253, 27
	s_ashr_i32 s9, s8, 31
	s_nop 0
	v_lshl_add_u64 v[8:9], s[10:11], 0, v[8:9]
	v_lshl_add_u64 v[8:9], s[8:9], 1, v[8:9]
	v_lshl_add_u64 v[8:9], v[8:9], 0, v[136:137]
	global_store_dwordx4 v[8:9], v[18:21], off
	s_branch .LBB0_94

; DI unsigned pk2(float lo, float hi) { return f2bf(lo) | (f2bf(hi) << 16); }
; DI void conv_T(const float* src, int K, int N, bf16_t* dst, int grp, int gstride, int goff, LAS float* tile) {
;     ...
;         {
;             const int nn = tid >> 3, k8 = (tid & 7) * 8, n = n0 + nn;
;             if (n < N) {
;                 float x[8];
; #pragma unroll
;                 for (int j = 0; j < 8; ++j) x[j] = tile[(k8 + j) * 65 + nn];
;                 u32x4 w; w.x = pk2(x[0], x[1]); w.y = pk2(x[2], x[3]); w.z = pk2(x[4], x[5]); w.w = pk2(x[6], x[7]);
;                 const size_t row = (size_t)(n / grp) * gstride + (n % grp) + goff;
;                 *(u32x4*)(dst + row * K + k0 + k8) = w;
;             }
.LBB0_116:
	s_ashr_i32 s4, s10, 31
	s_lshr_b32 s4, s4, 28
	s_add_i32 s4, s10, s4
	s_ashr_i32 s10, s4, 4
	s_waitcnt lgkmcnt(0)
	s_barrier
	v_add_u32_e32 v8, s8, v13
	s_lshl_b32 s4, s10, 10
	v_subrev_u32_e32 v8, s4, v8
	v_cmp_gt_i32_e32 vcc, s31, v8
	s_and_saveexec_b64 s[4:5], vcc
	s_cbranch_execz .LBB0_109
	ds_read2_b32 v[10:11], v16 offset1:65
	ds_read2_b32 v[20:21], v16 offset0:130 offset1:195
	v_add_u32_e32 v9, 0x400, v16
	ds_read2_b32 v[22:23], v9 offset0:4 offset1:69
	ds_read2_b32 v[24:25], v9 offset0:134 offset1:199
	v_readlane_b32 s12, v253, 31
	s_waitcnt lgkmcnt(3)
	s_nop 0
	s_nop 0
	s_nop 0
	v_cvt_pk_bf16_f32 v18, v10, v11
	s_waitcnt lgkmcnt(2)
	v_cvt_pk_bf16_f32 v19, v20, v21
	s_waitcnt lgkmcnt(1)
	v_cvt_pk_bf16_f32 v20, v22, v23
	s_waitcnt lgkmcnt(0)
	v_cvt_pk_bf16_f32 v9, v24, v24
	v_lshrrev_b32_e32 v9, 16, v9
	v_cvt_pk_bf16_f32 v10, v25, v25
	v_and_or_b32 v21, v10, s39, v9
	v_ashrrev_i32_e32 v9, 31, v8
	v_lshrrev_b32_e32 v9, 2, v9
	v_add_u32_e32 v9, v8, v9
	v_and_b32_e32 v9, -2.0, v9
	v_sub_u32_e32 v8, v8, v9
	v_ashrrev_i32_e32 v9, 31, v8
	s_lshl_b32 s10, s10, 6
	v_lshlrev_b64 v[8:9], 9, v[8:9]
	v_readlane_b32 s13, v253, 32
	s_ashr_i32 s11, s10, 31
	s_nop 0
	v_lshl_add_u64 v[8:9], s[12:13], 0, v[8:9]
	v_lshl_add_u64 v[8:9], s[10:11], 1, v[8:9]
	v_lshl_add_u64 v[8:9], v[8:9], 0, v[136:137]
	global_store_dwordx4 v[8:9], v[18:21], off
	s_branch .LBB0_109

; DI unsigned pk2(float lo, float hi) { return f2bf(lo) | (f2bf(hi) << 16); }
; DI void conv_T(const float* src, int K, int N, bf16_t* dst, int grp, int gstride, int goff, LAS float* tile) {
;     ...
;         {
;             const int nn = tid >> 3, k8 = (tid & 7) * 8, n = n0 + nn;
;             if (n < N) {
;                 float x[8];
; #pragma unroll
;                 for (int j = 0; j < 8; ++j) x[j] = tile[(k8 + j) * 65 + nn];
;                 u32x4 w; w.x = pk2(x[0], x[1]); w.y = pk2(x[2], x[3]); w.z = pk2(x[4], x[5]); w.w = pk2(x[6], x[7]);
;                 const size_t row = (size_t)(n / grp) * gstride + (n % grp) + goff;
;                 *(u32x4*)(dst + row * K + k0 + k8) = w;
;             }
.LBB0_131:
	s_ashr_i32 s6, s12, 31
	s_lshr_b32 s6, s6, 28
	s_add_i32 s6, s12, s6
	s_ashr_i32 s12, s6, 4
	s_waitcnt lgkmcnt(0)
	s_barrier
	v_add_u32_e32 v8, s10, v13
	s_lshl_b32 s6, s12, 10
	v_subrev_u32_e32 v8, s6, v8
	v_cmp_gt_i32_e32 vcc, s31, v8
	s_and_saveexec_b64 s[6:7], vcc
	s_cbranch_execz .LBB0_124
	ds_read2_b32 v[10:11], v16 offset1:65
	ds_read2_b32 v[20:21], v16 offset0:130 offset1:195
	v_add_u32_e32 v9, 0x400, v16
	ds_read2_b32 v[22:23], v9 offset0:4 offset1:69
	ds_read2_b32 v[24:25], v9 offset0:134 offset1:199
	v_readlane_b32 s14, v253, 33
	s_waitcnt lgkmcnt(3)
	s_nop 0
	s_nop 0
	s_nop 0
	v_cvt_pk_bf16_f32 v18, v10, v11
	s_waitcnt lgkmcnt(2)
	v_cvt_pk_bf16_f32 v19, v20, v21
	s_waitcnt lgkmcnt(1)
	v_cvt_pk_bf16_f32 v20, v22, v23
	s_waitcnt lgkmcnt(0)
	v_cvt_pk_bf16_f32 v9, v24, v24
	v_lshrrev_b32_e32 v9, 16, v9
	v_cvt_pk_bf16_f32 v10, v25, v25
	v_and_or_b32 v21, v10, s39, v9
	v_ashrrev_i32_e32 v9, 31, v8
	v_lshrrev_b32_e32 v9, 2, v9
	v_add_u32_e32 v9, v8, v9
	v_and_b32_e32 v9, -2.0, v9
	v_sub_u32_e32 v8, v8, v9
	v_ashrrev_i32_e32 v9, 31, v8
	s_lshl_b32 s12, s12, 6
	v_lshlrev_b64 v[8:9], 11, v[8:9]
	v_readlane_b32 s15, v253, 34
	s_ashr_i32 s13, s12, 31
	s_nop 0
	v_lshl_add_u64 v[8:9], s[14:15], 0, v[8:9]
	v_lshl_add_u64 v[8:9], s[12:13], 1, v[8:9]
	v_lshl_add_u64 v[8:9], v[8:9], 0, v[136:137]
	global_store_dwordx4 v[8:9], v[18:21], off
	s_branch .LBB0_124

; DI unsigned pk2(float lo, float hi) { return f2bf(lo) | (f2bf(hi) << 16); }
; DI void conv_T(const float* src, int K, int N, bf16_t* dst, int grp, int gstride, int goff, LAS float* tile) {
;     ...
;         {
;             const int nn = tid >> 3, k8 = (tid & 7) * 8, n = n0 + nn;
;             if (n < N) {
;                 float x[8];
; #pragma unroll
;                 for (int j = 0; j < 8; ++j) x[j] = tile[(k8 + j) * 65 + nn];
;                 u32x4 w; w.x = pk2(x[0], x[1]); w.y = pk2(x[2], x[3]); w.z = pk2(x[4], x[5]); w.w = pk2(x[6], x[7]);
;                 const size_t row = (size_t)(n / grp) * gstride + (n % grp) + goff;
;                 *(u32x4*)(dst + row * K + k0 + k8) = w;
;             }
.LBB0_146:
	s_ashr_i32 s4, s10, 31
	s_lshr_b32 s4, s4, 28
	s_add_i32 s4, s10, s4
	s_ashr_i32 s10, s4, 4
	s_waitcnt lgkmcnt(0)
	s_barrier
	v_add_u32_e32 v8, s8, v13
	s_lshl_b32 s4, s10, 10
	v_subrev_u32_e32 v8, s4, v8
	v_cmp_gt_i32_e32 vcc, s31, v8
	s_and_saveexec_b64 s[4:5], vcc
	s_cbranch_execz .LBB0_139
	ds_read2_b32 v[10:11], v16 offset1:65
	ds_read2_b32 v[20:21], v16 offset0:130 offset1:195
	v_add_u32_e32 v9, 0x400, v16
	ds_read2_b32 v[22:23], v9 offset0:4 offset1:69
	ds_read2_b32 v[24:25], v9 offset0:134 offset1:199
	v_readlane_b32 s12, v253, 35
	s_waitcnt lgkmcnt(3)
	s_nop 0
	s_nop 0
	s_nop 0
	v_cvt_pk_bf16_f32 v18, v10, v11
	s_waitcnt lgkmcnt(2)
	v_cvt_pk_bf16_f32 v19, v20, v21
	s_waitcnt lgkmcnt(1)
	v_cvt_pk_bf16_f32 v20, v22, v23
	s_waitcnt lgkmcnt(0)
	v_cvt_pk_bf16_f32 v9, v24, v24
	v_lshrrev_b32_e32 v9, 16, v9
	v_cvt_pk_bf16_f32 v10, v25, v25
	v_and_or_b32 v21, v10, s39, v9
	v_ashrrev_i32_e32 v9, 31, v8
	v_lshrrev_b32_e32 v9, 2, v9
	v_add_u32_e32 v9, v8, v9
	v_and_b32_e32 v9, -2.0, v9
	v_sub_u32_e32 v8, v8, v9
	v_ashrrev_i32_e32 v9, 31, v8
	s_lshl_b32 s10, s10, 6
	v_lshlrev_b64 v[8:9], 9, v[8:9]
	v_readlane_b32 s13, v253, 36
	s_ashr_i32 s11, s10, 31
	s_nop 0
	v_lshl_add_u64 v[8:9], s[12:13], 0, v[8:9]
	v_lshl_add_u64 v[8:9], s[10:11], 1, v[8:9]
	v_lshl_add_u64 v[8:9], v[8:9], 0, v[136:137]
	global_store_dwordx4 v[8:9], v[18:21], off
	s_branch .LBB0_139

; DI unsigned pk2(float lo, float hi) { return f2bf(lo) | (f2bf(hi) << 16); }
; DI void conv_T(const float* src, int K, int N, bf16_t* dst, int grp, int gstride, int goff, LAS float* tile) {
;     ...
;         {
;             const int nn = tid >> 3, k8 = (tid & 7) * 8, n = n0 + nn;
;             if (n < N) {
;                 float x[8];
; #pragma unroll
;                 for (int j = 0; j < 8; ++j) x[j] = tile[(k8 + j) * 65 + nn];
;                 u32x4 w; w.x = pk2(x[0], x[1]); w.y = pk2(x[2], x[3]); w.z = pk2(x[4], x[5]); w.w = pk2(x[6], x[7]);
;                 const size_t row = (size_t)(n / grp) * gstride + (n % grp) + goff;
;                 *(u32x4*)(dst + row * K + k0 + k8) = w;
;             }
.LBB0_161:
	s_mul_hi_i32 s4, s10, 0x92492493
	s_add_i32 s4, s4, s10
	s_lshr_b32 s5, s4, 31
	s_ashr_i32 s10, s4, 4
	s_add_i32 s10, s10, s5
	s_mul_i32 s4, s10, 0xfffff900
	s_waitcnt lgkmcnt(0)
	s_barrier
	s_add_i32 s4, s4, s8
	v_add_u32_e32 v8, s4, v11
	s_movk_i32 s4, 0x700
	v_cmp_gt_i32_e32 vcc, s4, v8
	s_and_saveexec_b64 s[4:5], vcc
	s_cbranch_execz .LBB0_154
	ds_read2_b32 v[16:17], v14 offset1:65
	ds_read2_b32 v[18:19], v14 offset0:130 offset1:195
	v_add_u32_e32 v9, 0x400, v14
	ds_read2_b32 v[20:21], v9 offset0:4 offset1:69
	ds_read2_b32 v[22:23], v9 offset0:134 offset1:199
	v_readlane_b32 s12, v253, 57
	s_waitcnt lgkmcnt(3)
	s_nop 0
	s_nop 0
	s_nop 0
	v_cvt_pk_bf16_f32 v16, v16, v17
	s_waitcnt lgkmcnt(2)
	v_cvt_pk_bf16_f32 v17, v18, v19
	s_waitcnt lgkmcnt(1)
	v_cvt_pk_bf16_f32 v18, v20, v21
	s_waitcnt lgkmcnt(0)
	v_cvt_pk_bf16_f32 v9, v22, v22
	v_lshrrev_b32_e32 v9, 16, v9
	v_cvt_pk_bf16_f32 v15, v23, v23
	v_and_or_b32 v19, v15, s39, v9
	v_ashrrev_i32_e32 v9, 31, v8
	v_lshrrev_b32_e32 v9, 2, v9
	v_add_u32_e32 v9, v8, v9
	v_and_b32_e32 v9, -2.0, v9
	v_sub_u32_e32 v8, v8, v9
	v_ashrrev_i32_e32 v9, 31, v8
	s_lshl_b32 s10, s10, 6
	v_lshlrev_b64 v[8:9], 11, v[8:9]
	v_readlane_b32 s13, v253, 58
	s_ashr_i32 s11, s10, 31
	s_nop 0
	v_lshl_add_u64 v[8:9], s[12:13], 0, v[8:9]
	v_lshl_add_u64 v[8:9], s[10:11], 1, v[8:9]
	v_lshl_add_u64 v[8:9], v[8:9], 0, v[136:137]
	global_store_dwordx4 v[8:9], v[16:19], off
	s_branch .LBB0_154

; DI unsigned pk2(float lo, float hi) { return f2bf(lo) | (f2bf(hi) << 16); }
; DI void conv_T(const float* src, int K, int N, bf16_t* dst, int grp, int gstride, int goff, LAS float* tile) {
;     ...
;         {
;             const int nn = tid >> 3, k8 = (tid & 7) * 8, n = n0 + nn;
;             if (n < N) {
;                 float x[8];
; #pragma unroll
;                 for (int j = 0; j < 8; ++j) x[j] = tile[(k8 + j) * 65 + nn];
;                 u32x4 w; w.x = pk2(x[0], x[1]); w.y = pk2(x[2], x[3]); w.z = pk2(x[4], x[5]); w.w = pk2(x[6], x[7]);
;                 const size_t row = (size_t)(n / grp) * gstride + (n % grp) + goff;
;                 *(u32x4*)(dst + row * K + k0 + k8) = w;
;             }
.LBB0_176:
	s_ashr_i32 s2, s8, 31
	s_lshr_b32 s2, s2, 28
	s_add_i32 s2, s8, s2
	s_ashr_i32 s8, s2, 4
	s_waitcnt lgkmcnt(0)
	s_barrier
	v_add_u32_e32 v8, s6, v13
	s_lshl_b32 s2, s8, 10
	v_subrev_u32_e32 v8, s2, v8
	v_cmp_gt_i32_e32 vcc, s31, v8
	s_and_saveexec_b64 s[2:3], vcc
	s_cbranch_execz .LBB0_169
	ds_read2_b32 v[10:11], v16 offset1:65
	ds_read2_b32 v[20:21], v16 offset0:130 offset1:195
	v_add_u32_e32 v9, 0x400, v16
	ds_read2_b32 v[22:23], v9 offset0:4 offset1:69
	ds_read2_b32 v[24:25], v9 offset0:134 offset1:199
	v_readlane_b32 s10, v253, 63
	s_waitcnt lgkmcnt(3)
	s_nop 0
	s_nop 0
	s_nop 0
	v_cvt_pk_bf16_f32 v18, v10, v11
	s_waitcnt lgkmcnt(2)
	v_cvt_pk_bf16_f32 v19, v20, v21
	s_waitcnt lgkmcnt(1)
	v_cvt_pk_bf16_f32 v20, v22, v23
	s_waitcnt lgkmcnt(0)
	v_cvt_pk_bf16_f32 v9, v24, v24
	v_lshrrev_b32_e32 v9, 16, v9
	v_cvt_pk_bf16_f32 v10, v25, v25
	v_and_or_b32 v21, v10, s39, v9
	v_ashrrev_i32_e32 v9, 31, v8
	v_lshrrev_b32_e32 v9, 2, v9
	v_add_u32_e32 v9, v8, v9
	v_and_b32_e32 v9, -2.0, v9
	v_sub_u32_e32 v8, v8, v9
	v_ashrrev_i32_e32 v9, 31, v8
	s_lshl_b32 s8, s8, 6
	v_lshlrev_b64 v[8:9], 11, v[8:9]
	v_readlane_b32 s11, v254, 0
	s_ashr_i32 s9, s8, 31
	s_nop 0
	v_lshl_add_u64 v[8:9], s[10:11], 0, v[8:9]
	v_lshl_add_u64 v[8:9], s[8:9], 1, v[8:9]
	v_lshl_add_u64 v[8:9], v[8:9], 0, v[136:137]
	global_store_dwordx4 v[8:9], v[18:21], off
	s_branch .LBB0_169

; DI unsigned pk2(float lo, float hi) { return f2bf(lo) | (f2bf(hi) << 16); }
; DI void conv_T(const float* src, int K, int N, bf16_t* dst, int grp, int gstride, int goff, LAS float* tile) {
;     ...
;         {
;             const int nn = tid >> 3, k8 = (tid & 7) * 8, n = n0 + nn;
;             if (n < N) {
;                 float x[8];
; #pragma unroll
;                 for (int j = 0; j < 8; ++j) x[j] = tile[(k8 + j) * 65 + nn];
;                 u32x4 w; w.x = pk2(x[0], x[1]); w.y = pk2(x[2], x[3]); w.z = pk2(x[4], x[5]); w.w = pk2(x[6], x[7]);
;                 const size_t row = (size_t)(n / grp) * gstride + (n % grp) + goff;
;                 *(u32x4*)(dst + row * K + k0 + k8) = w;
;             }
.LBB0_191:
	s_mul_hi_i32 s2, s8, 0x7e07e07f
	s_lshr_b32 s3, s2, 31
	s_ashr_i32 s8, s2, 5
	s_add_i32 s8, s8, s3
	s_mul_i32 s2, s8, 0xffffefc0
	s_waitcnt lgkmcnt(0)
	s_barrier
	s_add_i32 s2, s2, s6
	v_add_u32_e32 v8, s2, v11
	s_movk_i32 s2, 0x1010
	v_cmp_gt_i32_e32 vcc, s2, v8
	s_and_saveexec_b64 s[2:3], vcc
	s_cbranch_execz .LBB0_184
	ds_read2_b32 v[16:17], v14 offset1:65
	ds_read2_b32 v[18:19], v14 offset0:130 offset1:195
	v_add_u32_e32 v9, 0x400, v14
	ds_read2_b32 v[20:21], v9 offset0:4 offset1:69
	ds_read2_b32 v[22:23], v9 offset0:134 offset1:199
	v_readlane_b32 s10, v254, 1
	s_waitcnt lgkmcnt(3)
	s_nop 0
	s_nop 0
	s_nop 0
	v_cvt_pk_bf16_f32 v16, v16, v17
	s_waitcnt lgkmcnt(2)
	v_cvt_pk_bf16_f32 v17, v18, v19
	s_waitcnt lgkmcnt(1)
	v_cvt_pk_bf16_f32 v18, v20, v21
	s_waitcnt lgkmcnt(0)
	v_cvt_pk_bf16_f32 v9, v22, v22
	v_lshrrev_b32_e32 v9, 16, v9
	v_cvt_pk_bf16_f32 v15, v23, v23
	v_and_or_b32 v19, v15, s39, v9
	v_ashrrev_i32_e32 v9, 31, v8
	v_lshrrev_b32_e32 v9, 2, v9
	v_add_u32_e32 v9, v8, v9
	v_and_b32_e32 v9, -2.0, v9
	v_sub_u32_e32 v8, v8, v9
	v_ashrrev_i32_e32 v9, 31, v8
	s_lshl_b32 s8, s8, 6
	v_lshlrev_b64 v[8:9], 11, v[8:9]
	v_readlane_b32 s11, v254, 2
	s_ashr_i32 s9, s8, 31
	s_nop 0
	v_lshl_add_u64 v[8:9], s[10:11], 0, v[8:9]
	v_lshl_add_u64 v[8:9], s[8:9], 1, v[8:9]
	v_lshl_add_u64 v[8:9], v[8:9], 0, v[136:137]
	global_store_dwordx4 v[8:9], v[16:19], off
	s_branch .LBB0_184

; DI unsigned pk2(float lo, float hi) { return f2bf(lo) | (f2bf(hi) << 16); }
; DI void lds_barrier() { asm volatile("s_waitcnt lgkmcnt(0)" ::: "memory"); __builtin_amdgcn_s_barrier(); asm volatile("" ::: "memory"); }
; DI void conv_T(const float* src, int K, int N, bf16_t* dst, int grp, int gstride, int goff, LAS float* tile) {
;     ...
;         lds_barrier();
;         {
;             const int nn = tid >> 3, k8 = (tid & 7) * 8, n = n0 + nn;
;             if (n < N) {
;                 float x[8];
; #pragma unroll
;                 for (int j = 0; j < 8; ++j) x[j] = tile[(k8 + j) * 65 + nn];
;                 u32x4 w; w.x = pk2(x[0], x[1]); w.y = pk2(x[2], x[3]); w.z = pk2(x[4], x[5]); w.w = pk2(x[6], x[7]);
;                 const size_t row = (size_t)(n / grp) * gstride + (n % grp) + goff;
;                 *(u32x4*)(dst + row * K + k0 + k8) = w;
;             }
.LBB0_206:
	s_ashr_i32 s2, s8, 31
	s_lshr_b32 s2, s2, 28
	s_add_i32 s2, s8, s2
	s_ashr_i32 s8, s2, 4
	s_waitcnt lgkmcnt(0)
	s_barrier
	v_add_u32_e32 v8, s6, v13
	s_lshl_b32 s2, s8, 10
	v_subrev_u32_e32 v8, s2, v8
	v_cmp_gt_i32_e32 vcc, s31, v8
	s_and_saveexec_b64 s[2:3], vcc
	s_cbranch_execz .LBB0_199
	ds_read2_b32 v[10:11], v16 offset1:65
	ds_read2_b32 v[20:21], v16 offset0:130 offset1:195
	v_add_u32_e32 v9, 0x400, v16
	ds_read2_b32 v[22:23], v9 offset0:4 offset1:69
	ds_read2_b32 v[24:25], v9 offset0:134 offset1:199
	v_readlane_b32 s10, v254, 7
	s_waitcnt lgkmcnt(3)
	s_nop 0
	s_nop 0
	s_nop 0
	v_cvt_pk_bf16_f32 v18, v10, v11
	s_waitcnt lgkmcnt(2)
	v_cvt_pk_bf16_f32 v19, v20, v21
	s_waitcnt lgkmcnt(1)
	v_cvt_pk_bf16_f32 v20, v22, v23
	s_waitcnt lgkmcnt(0)
	v_cvt_pk_bf16_f32 v9, v24, v24
	v_lshrrev_b32_e32 v9, 16, v9
	v_cvt_pk_bf16_f32 v10, v25, v25
	v_and_or_b32 v21, v10, s39, v9
	v_ashrrev_i32_e32 v9, 31, v8
	v_lshrrev_b32_e32 v9, 2, v9
	v_add_u32_e32 v9, v8, v9
	v_and_b32_e32 v9, -2.0, v9
	v_sub_u32_e32 v8, v8, v9
	v_ashrrev_i32_e32 v9, 31, v8
	s_lshl_b32 s8, s8, 6
	v_lshlrev_b64 v[8:9], 11, v[8:9]
	v_readlane_b32 s11, v254, 8
	s_ashr_i32 s9, s8, 31
	s_nop 0
	v_lshl_add_u64 v[8:9], s[10:11], 0, v[8:9]
	v_lshl_add_u64 v[8:9], s[8:9], 1, v[8:9]
	v_lshl_add_u64 v[8:9], v[8:9], 0, v[136:137]
	global_store_dwordx4 v[8:9], v[18:21], off
	s_branch .LBB0_199

; DI unsigned pk2(float lo, float hi) { return f2bf(lo) | (f2bf(hi) << 16); }
; DI void lds_barrier() { asm volatile("s_waitcnt lgkmcnt(0)" ::: "memory"); __builtin_amdgcn_s_barrier(); asm volatile("" ::: "memory"); }
; DI void conv_T(const float* src, int K, int N, bf16_t* dst, int grp, int gstride, int goff, LAS float* tile) {
;     ...
;         lds_barrier();
;         {
;             const int nn = tid >> 3, k8 = (tid & 7) * 8, n = n0 + nn;
;             if (n < N) {
;                 float x[8];
; #pragma unroll
;                 for (int j = 0; j < 8; ++j) x[j] = tile[(k8 + j) * 65 + nn];
;                 u32x4 w; w.x = pk2(x[0], x[1]); w.y = pk2(x[2], x[3]); w.z = pk2(x[4], x[5]); w.w = pk2(x[6], x[7]);
;                 const size_t row = (size_t)(n / grp) * gstride + (n % grp) + goff;
;                 *(u32x4*)(dst + row * K + k0 + k8) = w;
;             }
.LBB0_216:
	s_waitcnt lgkmcnt(0)
	s_barrier
	s_and_saveexec_b64 s[4:5], s[0:1]
	s_cbranch_execz .LBB0_213
	ds_read2_b32 v[16:17], v14 offset1:65
	ds_read2_b32 v[18:19], v14 offset0:130 offset1:195
	v_add_u32_e32 v15, 0x400, v14
	ds_read2_b32 v[20:21], v15 offset0:4 offset1:69
	ds_read2_b32 v[22:23], v15 offset0:134 offset1:199
	s_add_i32 s12, s27, s6
	s_waitcnt lgkmcnt(3)
	v_cvt_pk_bf16_f32 v16, v16, v17
	s_waitcnt lgkmcnt(2)
	v_cvt_pk_bf16_f32 v17, v18, v19
	s_waitcnt lgkmcnt(1)
	v_cvt_pk_bf16_f32 v18, v20, v21
	s_waitcnt lgkmcnt(0)
	v_cvt_pk_bf16_f32 v15, v22, v22
	v_lshrrev_b32_e32 v15, 16, v15
	v_cvt_pk_bf16_f32 v19, v23, v23
	s_ashr_i32 s13, s12, 31
	v_and_or_b32 v19, v19, s39, v15
	v_lshl_add_u64 v[20:21], s[12:13], 1, v[10:11]
	global_store_dwordx4 v[20:21], v[16:19], off
	s_branch .LBB0_213

; DI unsigned pk2(float lo, float hi) { return f2bf(lo) | (f2bf(hi) << 16); }
; DI void lds_barrier() { asm volatile("s_waitcnt lgkmcnt(0)" ::: "memory"); __builtin_amdgcn_s_barrier(); asm volatile("" ::: "memory"); }
; DI void conv_T(const float* src, int K, int N, bf16_t* dst, int grp, int gstride, int goff, LAS float* tile) {
;     ...
;         lds_barrier();
;         {
;             const int nn = tid >> 3, k8 = (tid & 7) * 8, n = n0 + nn;
;             if (n < N) {
;                 float x[8];
; #pragma unroll
;                 for (int j = 0; j < 8; ++j) x[j] = tile[(k8 + j) * 65 + nn];
;                 u32x4 w; w.x = pk2(x[0], x[1]); w.y = pk2(x[2], x[3]); w.z = pk2(x[4], x[5]); w.w = pk2(x[6], x[7]);
;                 const size_t row = (size_t)(n / grp) * gstride + (n % grp) + goff;
;                 *(u32x4*)(dst + row * K + k0 + k8) = w;
;             }
.LBB0_222:
	s_waitcnt lgkmcnt(0)
	s_barrier
	s_and_saveexec_b64 s[6:7], s[2:3]
	s_cbranch_execz .LBB0_219
	ds_read2_b32 v[16:17], v14 offset1:65
	ds_read2_b32 v[18:19], v14 offset0:130 offset1:195
	v_add_u32_e32 v15, 0x400, v14
	ds_read2_b32 v[20:21], v15 offset0:4 offset1:69
	ds_read2_b32 v[22:23], v15 offset0:134 offset1:199
	s_add_i32 s14, s27, s9
	s_waitcnt lgkmcnt(3)
	v_cvt_pk_bf16_f32 v16, v16, v17
	s_waitcnt lgkmcnt(2)
	v_cvt_pk_bf16_f32 v17, v18, v19
	s_waitcnt lgkmcnt(1)
	v_cvt_pk_bf16_f32 v18, v20, v21
	s_waitcnt lgkmcnt(0)
	v_cvt_pk_bf16_f32 v15, v22, v22
	v_lshrrev_b32_e32 v15, 16, v15
	v_cvt_pk_bf16_f32 v19, v23, v23
	s_ashr_i32 s15, s14, 31
	v_and_or_b32 v19, v19, s39, v15
	v_lshl_add_u64 v[20:21], s[14:15], 1, v[10:11]
	global_store_dwordx4 v[20:21], v[16:19], off
	s_branch .LBB0_219

; DI float bflo(unsigned w) { return __uint_as_float(w << 16); }
; DI float bfhi(unsigned w) { return __uint_as_float(w & 0xffff0000u); }
; DI float wave_sum(float v) { v = row16_sum(v); return (rdlane(v, 0) + rdlane(v, 16)) + (rdlane(v, 32) + rdlane(v, 48)); }
; DI void phase_ln(const bf16_t* vin, float* xf, bf16_t* xb, const float* g, const float* b, bool write_f32) {
;     ...
;             for (int i = 0; i < 4; ++i) { const u32x2 w = *(const u32x2*)(row + i * 256 + lane * 4); v[k][i] = (f32x4){bflo(w.x), bfhi(w.x), bflo(w.y), bfhi(w.y)}; }
;         }
; #pragma unroll
;         for (int k = 0; k < R; ++k) {
;             float s = 0.f;
; #pragma unroll
;             for (int i = 0; i < 4; ++i) s += (v[k][i][0] + v[k][i][1]) + (v[k][i][2] + v[k][i][3]);
;             const float mean = wave_sum(s) * (1.0f / 1024.0f);
;             float q = 0.f;
; #pragma unroll
;             for (int i = 0; i < 4; ++i) { const f32x4 d = v[k][i] - mean; q += (d[0] * d[0] + d[1] * d[1]) + (d[2] * d[2] + d[3] * d[3]); }
.Lln_nopf:
	v_lshl_add_u64 v[46:47], v[44:45], 0, v[136:137]
	v_mov_b64_e32 v[110:111], v[208:209]
	v_mov_b64_e32 v[112:113], v[210:211]
	v_mov_b64_e32 v[48:49], v[212:213]
	s_mul_i32 s0, s50, 24
	v_mov_b64_e32 v[46:47], v[214:215]
	v_lshl_add_u64 v[126:127], v[38:39], 0, v[136:137]
	v_lshl_add_u64 v[38:39], v[38:39], 0, s[14:15]
	v_lshl_add_u64 v[44:45], v[44:45], 0, s[14:15]
	v_lshlrev_b32_e32 v119, 16, v111
	v_lshlrev_b32_e32 v118, 16, v110
	v_lshlrev_b32_e32 v104, 16, v48
	v_and_b32_e32 v105, 0xffff0000, v48
	v_lshlrev_b32_e32 v103, 16, v46
	v_and_b32_e32 v99, 0xffff0000, v46
	v_lshlrev_b32_e32 v101, 16, v47
	v_and_b32_e32 v97, 0xffff0000, v47
	v_lshl_add_u64 v[46:47], v[40:41], 0, v[136:137]
	v_lshlrev_b32_e32 v106, 16, v49
	v_and_b32_e32 v107, 0xffff0000, v49
	v_mov_b64_e32 v[108:109], v[216:217]
	v_mov_b64_e32 v[94:95], v[218:219]
	v_mov_b64_e32 v[48:49], v[220:221]
	v_and_b32_e32 v111, 0xffff0000, v111
	v_mov_b64_e32 v[46:47], v[222:223]
	v_and_b32_e32 v110, 0xffff0000, v110
	v_pk_add_f32 v[114:115], v[118:119], v[110:111]
	v_lshlrev_b32_e32 v117, 16, v113
	v_lshlrev_b32_e32 v116, 16, v112
	v_and_b32_e32 v113, 0xffff0000, v113
	v_and_b32_e32 v112, 0xffff0000, v112
	v_add_f32_e32 v33, v114, v115
	v_pk_add_f32 v[114:115], v[116:117], v[112:113]
	v_add_f32_e32 v102, 0, v33
	v_pk_add_f32 v[114:115], v[114:115], v[114:115] op_sel:[0,1] op_sel_hi:[1,0]
	v_add_f32_e32 v100, v104, v105
	v_add_f32_e32 v96, v106, v107
	v_mov_b32_e32 v115, v99
	v_pk_add_f32 v[114:115], v[102:103], v[114:115]
	v_pk_add_f32 v[120:121], v[100:101], v[96:97]
	v_lshl_add_u64 v[40:41], v[40:41], 0, s[14:15]
	v_pk_add_f32 v[114:115], v[114:115], v[120:121]
	v_lshlrev_b32_e32 v86, 16, v48
	v_and_b32_e32 v87, 0xffff0000, v48
	v_lshlrev_b32_e32 v85, 16, v46
	v_and_b32_e32 v81, 0xffff0000, v46
	v_add_u32_e32 v46, s34, v32
	v_lshlrev_b32_e32 v83, 16, v47
	v_and_b32_e32 v79, 0xffff0000, v47
	v_ashrrev_i32_e32 v47, 31, v46
	v_lshlrev_b64 v[72:73], 11, v[46:47]
	v_lshl_add_u64 v[46:47], v[34:35], 0, v[72:73]
	v_lshlrev_b32_e32 v88, 16, v49
	v_and_b32_e32 v89, 0xffff0000, v49
	v_mov_b64_e32 v[92:93], v[224:225]
	v_mov_b64_e32 v[90:91], v[226:227]
	v_mov_b64_e32 v[48:49], v[228:229]
	v_add_f32_e32 v33, v114, v115
	v_mov_b64_e32 v[46:47], v[230:231]
	v_add_f32_e32 v82, v86, v87
	v_add_f32_dpp v33, v33, v33 quad_perm:[1,0,3,2] row_mask:0xf bank_mask:0xf bound_ctrl:1
	v_add_f32_e32 v78, v88, v89
	v_pk_add_f32 v[128:129], v[82:83], v[78:79]
	v_add_f32_dpp v33, v33, v33 quad_perm:[2,3,0,1] row_mask:0xf bank_mask:0xf bound_ctrl:1
	v_lshl_add_u64 v[72:73], v[36:37], 0, v[72:73]
	v_lshlrev_b32_e32 v68, 16, v48
	v_and_b32_e32 v69, 0xffff0000, v48
	v_lshlrev_b32_e32 v67, 16, v46
	v_and_b32_e32 v63, 0xffff0000, v46
	v_add_u32_e32 v46, s0, v32
	v_lshlrev_b32_e32 v65, 16, v47
	v_and_b32_e32 v61, 0xffff0000, v47
	v_ashrrev_i32_e32 v47, 31, v46
	v_lshlrev_b64 v[58:59], 11, v[46:47]
	v_lshl_add_u64 v[46:47], v[34:35], 0, v[58:59]
	v_lshlrev_b32_e32 v70, 16, v49
	v_and_b32_e32 v71, 0xffff0000, v49
	v_mov_b64_e32 v[76:77], v[232:233]
	v_mov_b64_e32 v[74:75], v[234:235]
	v_mov_b64_e32 v[48:49], v[236:237]
	v_add_f32_dpp v33, v33, v33 row_half_mirror row_mask:0xf bank_mask:0xf bound_ctrl:1
	v_mov_b64_e32 v[46:47], v[238:239]
	v_add_f32_e32 v64, v68, v69
	v_add_f32_dpp v33, v33, v33 row_mirror row_mask:0xf bank_mask:0xf bound_ctrl:1
	v_add_f32_e32 v60, v70, v71
	v_readlane_b32 s8, v33, 16
	v_readlane_b32 s9, v33, 48
	v_readlane_b32 s0, v33, 0
	v_readlane_b32 s1, v33, 32
	v_mov_b32_e32 v114, s8
	v_mov_b32_e32 v115, s9
	v_pk_add_f32 v[114:115], s[0:1], v[114:115]
	v_lshl_add_u64 v[58:59], v[36:37], 0, v[58:59]
	v_add_f32_e32 v33, v114, v115
	v_fmac_f32_e32 v110, 0xba800000, v33
	v_fmac_f32_e32 v111, 0xba800000, v33
	v_fmac_f32_e32 v119, 0xba800000, v33
	v_fmac_f32_e32 v118, 0xba800000, v33
	v_mov_b32_e32 v122, v119
	v_mov_b32_e32 v123, v111
	v_mov_b32_e32 v119, v110
	v_pk_mul_f32 v[114:115], v[122:123], v[122:123]
	v_pk_mul_f32 v[110:111], v[118:119], v[118:119]
	v_fmac_f32_e32 v112, 0xba800000, v33
	v_pk_mov_b32 v[120:121], v[110:111], v[114:115] op_sel:[1,0]
	v_mov_b32_e32 v111, v115
	v_fmac_f32_e32 v113, 0xba800000, v33
	v_fmac_f32_e32 v117, 0xba800000, v33
	v_pk_add_f32 v[110:111], v[120:121], v[110:111]
	v_fmac_f32_e32 v116, 0xba800000, v33
	v_mov_b32_e32 v120, v117
	v_mov_b32_e32 v121, v113
	v_mov_b32_e32 v117, v112
	v_pk_mul_f32 v[114:115], v[120:121], v[120:121]
	v_pk_mul_f32 v[112:113], v[116:117], v[116:117]
	v_fmac_f32_e32 v104, 0xba800000, v33
	v_pk_mov_b32 v[124:125], v[112:113], v[114:115] op_sel:[1,0]
	v_mov_b32_e32 v113, v115
	v_fmac_f32_e32 v105, 0xba800000, v33
	v_fmac_f32_e32 v106, 0xba800000, v33
	v_pk_add_f32 v[112:113], v[124:125], v[112:113]
	v_fmac_f32_e32 v107, 0xba800000, v33
	v_pk_add_f32 v[110:111], v[110:111], v[110:111] op_sel_hi:[0,1]
	v_pk_add_f32 v[112:113], v[112:113], v[112:113] op_sel_hi:[0,1]
	v_fmac_f32_e32 v97, 0xba800000, v33
	v_fmac_f32_e32 v101, 0xba800000, v33
	v_fmac_f32_e32 v99, 0xba800000, v33
	v_fmac_f32_e32 v103, 0xba800000, v33
	v_mul_f32_e32 v110, v101, v101
	v_mul_f32_e32 v112, v97, v97
	v_pk_add_f32 v[110:111], v[110:111], v[112:113]
	v_and_b32_e32 v113, 0xffff0000, v109
	v_and_b32_e32 v112, 0xffff0000, v108
	v_mov_b32_e32 v98, v103
	v_mov_b32_e32 v96, v101
	v_add_u32_e32 v32, s54, v32
	v_lshlrev_b32_e32 v56, 16, v49
	v_and_b32_e32 v57, 0xffff0000, v49
	v_lshlrev_b32_e32 v53, 16, v46
	v_and_b32_e32 v49, 0xffff0000, v46
	v_lshlrev_b32_e32 v51, 16, v47
	v_and_b32_e32 v47, 0xffff0000, v47
	v_mul_f32_e32 v46, v104, v104
	v_pk_fma_f32 v[114:115], v[104:105], v[104:105], v[46:47] op_sel_hi:[1,1,0]
	v_mul_f32_e32 v46, v106, v106
; DI unsigned pk2(float lo, float hi) { return f2bf(lo) | (f2bf(hi) << 16); }
; DI float wave_sum(float v) { v = row16_sum(v); return (rdlane(v, 0) + rdlane(v, 16)) + (rdlane(v, 32) + rdlane(v, 48)); }
; DI void phase_ln(const bf16_t* vin, float* xf, bf16_t* xb, const float* g, const float* b, bool write_f32) {
;     ...
;             const float mean = wave_sum(s) * (1.0f / 1024.0f);
;             float q = 0.f;
; #pragma unroll
;             for (int i = 0; i < 4; ++i) { const f32x4 d = v[k][i] - mean; q += (d[0] * d[0] + d[1] * d[1]) + (d[2] * d[2] + d[3] * d[3]); }
;             const float rstd = rsqrtf(wave_sum(q) * (1.0f / 1024.0f) + 1e-5f);
;             float* row = xf + (size_t)(r0 + k * nw) * D_;
;             bf16_t* rb = xb + (size_t)(r0 + k * nw) * D_;
; #pragma unroll
;             for (int i = 0; i < 4; ++i) {
;                 const f32x4 o = (v[k][i] - mean) * rstd * gv[i] + bv[i];
;                 if (write_f32) *(f32x4*)(row + i * 256 + lane * 4) = o;
;                 u32x2 w; w.x = pk2(o[0], o[1]); w.y = pk2(o[2], o[3]);
;                 *(u32x2*)(rb + i * 256 + lane * 4) = w;
	v_pk_fma_f32 v[124:125], v[106:107], v[106:107], v[46:47] op_sel_hi:[1,1,0]
	v_mul_f32_e32 v114, v103, v103
	v_mul_f32_e32 v124, v99, v99
	v_pk_add_f32 v[114:115], v[114:115], v[124:125]
	v_lshlrev_b32_e32 v54, 16, v48
	v_pk_add_f32 v[110:111], v[114:115], v[110:111]
	v_and_b32_e32 v55, 0xffff0000, v48
	v_add_f32_e32 v33, v110, v111
	v_add_f32_e32 v50, v54, v55
	s_nop 0
	v_add_f32_dpp v33, v33, v33 quad_perm:[1,0,3,2] row_mask:0xf bank_mask:0xf bound_ctrl:1
	s_nop 1
	v_add_f32_dpp v33, v33, v33 quad_perm:[2,3,0,1] row_mask:0xf bank_mask:0xf bound_ctrl:1
	s_nop 1
	v_add_f32_dpp v33, v33, v33 row_half_mirror row_mask:0xf bank_mask:0xf bound_ctrl:1
	s_nop 1
	v_add_f32_dpp v33, v33, v33 row_mirror row_mask:0xf bank_mask:0xf bound_ctrl:1
	s_nop 0
	v_readlane_b32 s8, v33, 16
	v_readlane_b32 s9, v33, 48
	v_readlane_b32 s0, v33, 0
	v_readlane_b32 s1, v33, 32
	v_mov_b32_e32 v110, s8
	v_mov_b32_e32 v111, s9
	v_pk_add_f32 v[124:125], s[0:1], v[110:111]
	v_lshlrev_b32_e32 v111, 16, v109
	v_lshlrev_b32_e32 v110, 16, v108
	v_pk_add_f32 v[108:109], v[110:111], v[112:113]
	s_nop 0
	v_add_f32_e32 v33, v108, v109
	v_lshlrev_b32_e32 v109, 16, v95
	v_lshlrev_b32_e32 v108, 16, v94
	v_and_b32_e32 v95, 0xffff0000, v95
	v_and_b32_e32 v94, 0xffff0000, v94
	v_pk_add_f32 v[114:115], v[108:109], v[94:95]
	v_add_f32_e32 v84, 0, v33
	v_pk_add_f32 v[114:115], v[114:115], v[114:115] op_sel:[0,1] op_sel_hi:[1,0]
	s_nop 0
	v_mov_b32_e32 v115, v81
	v_pk_add_f32 v[114:115], v[84:85], v[114:115]
	v_and_b32_e32 v84, 0xffff0000, v90
	v_pk_add_f32 v[114:115], v[114:115], v[128:129]
	s_nop 0
	v_add_f32_e32 v33, v114, v115
	s_nop 1
	v_add_f32_dpp v33, v33, v33 quad_perm:[1,0,3,2] row_mask:0xf bank_mask:0xf bound_ctrl:1
	s_nop 1
	v_add_f32_dpp v33, v33, v33 quad_perm:[2,3,0,1] row_mask:0xf bank_mask:0xf bound_ctrl:1
	s_nop 1
	v_add_f32_dpp v33, v33, v33 row_half_mirror row_mask:0xf bank_mask:0xf bound_ctrl:1
	s_nop 1
	v_add_f32_dpp v33, v33, v33 row_mirror row_mask:0xf bank_mask:0xf bound_ctrl:1
	s_nop 0
	v_readlane_b32 s8, v33, 16
	v_readlane_b32 s9, v33, 48
	v_readlane_b32 s0, v33, 0
	v_readlane_b32 s1, v33, 32
	v_mov_b32_e32 v114, s8
	v_mov_b32_e32 v115, s9
	v_pk_add_f32 v[114:115], s[0:1], v[114:115]
	s_nop 0
	v_add_f32_e32 v33, v114, v115
	v_fmac_f32_e32 v112, 0xba800000, v33
	v_fmac_f32_e32 v113, 0xba800000, v33
	v_fmac_f32_e32 v111, 0xba800000, v33
	v_fmac_f32_e32 v110, 0xba800000, v33
	v_mov_b32_e32 v114, v111
	v_mov_b32_e32 v115, v113
	v_mov_b32_e32 v111, v112
	v_pk_mul_f32 v[128:129], v[114:115], v[114:115]
	v_pk_mul_f32 v[112:113], v[110:111], v[110:111]
	v_fmac_f32_e32 v94, 0xba800000, v33
	v_pk_mov_b32 v[130:131], v[112:113], v[128:129] op_sel:[1,0]
	v_mov_b32_e32 v113, v129
	v_pk_add_f32 v[112:113], v[130:131], v[112:113]
	v_fmac_f32_e32 v95, 0xba800000, v33
	v_fmac_f32_e32 v109, 0xba800000, v33
	v_pk_add_f32 v[128:129], v[112:113], v[112:113] op_sel_hi:[0,1]
	v_fmac_f32_e32 v108, 0xba800000, v33
	v_mov_b32_e32 v112, v109
	v_mov_b32_e32 v113, v95
	v_mov_b32_e32 v109, v94
	v_pk_mul_f32 v[130:131], v[112:113], v[112:113]
	v_pk_mul_f32 v[94:95], v[108:109], v[108:109]
	v_fmac_f32_e32 v86, 0xba800000, v33
	v_pk_mov_b32 v[132:133], v[94:95], v[130:131] op_sel:[1,0]
	v_mov_b32_e32 v95, v131
	v_fmac_f32_e32 v87, 0xba800000, v33
	v_fmac_f32_e32 v88, 0xba800000, v33
	v_mul_f32_e32 v46, v86, v86
	v_pk_add_f32 v[94:95], v[132:133], v[94:95]
	v_fmac_f32_e32 v89, 0xba800000, v33
	v_pk_fma_f32 v[130:131], v[86:87], v[86:87], v[46:47] op_sel_hi:[1,1,0]
	v_mul_f32_e32 v46, v88, v88
	v_pk_add_f32 v[94:95], v[94:95], v[94:95] op_sel_hi:[0,1]
	v_pk_fma_f32 v[132:133], v[88:89], v[88:89], v[46:47] op_sel_hi:[1,1,0]
	v_fmac_f32_e32 v79, 0xba800000, v33
	v_fmac_f32_e32 v83, 0xba800000, v33
	v_fmac_f32_e32 v81, 0xba800000, v33
	v_fmac_f32_e32 v85, 0xba800000, v33
	v_mul_f32_e32 v130, v85, v85
	v_mul_f32_e32 v132, v81, v81
	v_mul_f32_e32 v128, v83, v83
	v_mul_f32_e32 v94, v79, v79
	v_pk_add_f32 v[130:131], v[130:131], v[132:133]
	v_pk_add_f32 v[94:95], v[128:129], v[94:95]
	v_mov_b32_e32 v129, v124
	v_pk_add_f32 v[94:95], v[130:131], v[94:95]
	v_mov_b32_e32 v80, v85
	v_add_f32_e32 v33, v94, v95
	v_mov_b32_e32 v78, v83
	v_and_b32_e32 v85, 0xffff0000, v91
	v_add_f32_dpp v33, v33, v33 quad_perm:[1,0,3,2] row_mask:0xf bank_mask:0xf bound_ctrl:1
	s_nop 1
	v_add_f32_dpp v33, v33, v33 quad_perm:[2,3,0,1] row_mask:0xf bank_mask:0xf bound_ctrl:1
	s_nop 1
	v_add_f32_dpp v33, v33, v33 row_half_mirror row_mask:0xf bank_mask:0xf bound_ctrl:1
	s_nop 1
	v_add_f32_dpp v33, v33, v33 row_mirror row_mask:0xf bank_mask:0xf bound_ctrl:1
	s_nop 0
	v_readlane_b32 s8, v33, 16
	v_readlane_b32 s9, v33, 48
	v_readlane_b32 s0, v33, 0
	v_readlane_b32 s1, v33, 32
	v_mov_b32_e32 v94, s8
	v_mov_b32_e32 v95, s9
	v_pk_add_f32 v[94:95], s[0:1], v[94:95]
	s_mov_b32 s0, 0x3727c5ac
	v_mov_b32_e32 v128, v94
	v_mov_b32_e32 v124, v95
	v_pk_add_f32 v[124:125], v[128:129], v[124:125]
	v_mov_b64_e32 v[94:95], s[0:1]
	v_pk_fma_f32 v[124:125], v[124:125], s[18:19], v[94:95] op_sel_hi:[1,0,0]
	s_nop 0
	v_mul_f32_e32 v33, 0x4b800000, v125
	v_cmp_gt_f32_e64 s[0:1], s44, v125
	v_cmp_gt_f32_e32 vcc, s44, v124
	s_nop 0
	v_cndmask_b32_e64 v33, v125, v33, s[0:1]
	v_rsq_f32_e32 v33, v33
	s_nop 0
	v_mul_f32_e32 v46, 0x45800000, v33
	v_cndmask_b32_e64 v46, v33, v46, s[0:1]
	v_pk_mul_f32 v[118:119], v[118:119], v[46:47] op_sel_hi:[1,0]
	v_pk_mul_f32 v[122:123], v[122:123], v[46:47] op_sel_hi:[1,0]
	v_pk_fma_f32 v[118:119], v[0:1], v[118:119], v[8:9]
	v_pk_fma_f32 v[122:123], v[2:3], v[122:123], v[10:11]
	v_cvt_pk_bf16_f32 v118, v118, v119
	v_cvt_pk_bf16_f32 v33, v122, v122
	v_bfe_u32 v48, v123, 16, 1
	v_pk_mul_f32 v[116:117], v[116:117], v[46:47] op_sel_hi:[1,0]
; DI unsigned pk2(float lo, float hi) { return f2bf(lo) | (f2bf(hi) << 16); }
; DI float wave_sum(float v) { v = row16_sum(v); return (rdlane(v, 0) + rdlane(v, 16)) + (rdlane(v, 32) + rdlane(v, 48)); }
; DI void phase_ln(const bf16_t* vin, float* xf, bf16_t* xb, const float* g, const float* b, bool write_f32) {
;     ...
;             for (int i = 0; i < 4; ++i) { const f32x4 d = v[k][i] - mean; q += (d[0] * d[0] + d[1] * d[1]) + (d[2] * d[2] + d[3] * d[3]); }
;             const float rstd = rsqrtf(wave_sum(q) * (1.0f / 1024.0f) + 1e-5f);
;             float* row = xf + (size_t)(r0 + k * nw) * D_;
;             bf16_t* rb = xb + (size_t)(r0 + k * nw) * D_;
; #pragma unroll
;             for (int i = 0; i < 4; ++i) {
;                 const f32x4 o = (v[k][i] - mean) * rstd * gv[i] + bv[i];
;                 if (write_f32) *(f32x4*)(row + i * 256 + lane * 4) = o;
;                 u32x2 w; w.x = pk2(o[0], o[1]); w.y = pk2(o[2], o[3]);
;                 *(u32x2*)(rb + i * 256 + lane * 4) = w;
	v_lshrrev_b32_e32 v33, 16, v33
	v_add3_u32 v48, v123, v48, s68
	v_add_co_u32_e64 v122, s[0:1], s16, v126
	v_pk_fma_f32 v[116:117], v[4:5], v[116:117], v[12:13]
	v_and_or_b32 v119, v48, s39, v33
	v_addc_co_u32_e64 v123, s[0:1], 0, v127, s[0:1]
	s_nop 0
	global_store_dwordx2 v[122:123], v[118:119], off
	v_pk_mul_f32 v[118:119], v[120:121], v[46:47] op_sel_hi:[1,0]
	s_nop 0
	s_nop 0
	v_pk_fma_f32 v[118:119], v[6:7], v[118:119], v[14:15]
	v_cvt_pk_bf16_f32 v116, v116, v117
	v_pk_mul_f32 v[104:105], v[104:105], v[46:47] op_sel_hi:[1,0]
	v_pk_fma_f32 v[104:105], v[16:17], v[104:105], v[24:25]
	v_cvt_pk_bf16_f32 v117, v118, v119
	v_pk_mul_f32 v[106:107], v[106:107], v[46:47] op_sel_hi:[1,0]
	v_pk_fma_f32 v[106:107], v[18:19], v[106:107], v[26:27]
	v_cvt_pk_bf16_f32 v104, v104, v105
	v_pk_mul_f32 v[98:99], v[98:99], v[46:47] op_sel_hi:[1,0]
	v_pk_fma_f32 v[98:99], v[20:21], v[98:99], v[28:29]
	v_cvt_pk_bf16_f32 v105, v106, v107
	v_pk_mul_f32 v[96:97], v[96:97], v[46:47] op_sel_hi:[1,0]
	v_pk_fma_f32 v[96:97], v[22:23], v[96:97], v[30:31]
	v_cvt_pk_bf16_f32 v98, v98, v99
	s_nop 0
	s_nop 0
	v_cvt_pk_bf16_f32 v99, v96, v97
	v_mul_f32_e32 v33, 0x4b800000, v124
	v_cndmask_b32_e32 v33, v124, v33, vcc
	v_rsq_f32_e32 v33, v33
	global_store_dwordx2 v[122:123], v[98:99], off offset:1536
	v_lshl_add_u64 v[96:97], v[42:43], 0, v[136:137]
	global_store_dwordx2 v[122:123], v[116:117], off offset:512
	v_mul_f32_e32 v46, 0x45800000, v33
	v_cndmask_b32_e32 v46, v33, v46, vcc
	v_pk_mul_f32 v[98:99], v[110:111], v[46:47] op_sel_hi:[1,0]
	v_pk_mul_f32 v[100:101], v[114:115], v[46:47] op_sel_hi:[1,0]
	v_pk_fma_f32 v[98:99], v[0:1], v[98:99], v[8:9]
	v_pk_fma_f32 v[100:101], v[2:3], v[100:101], v[10:11]
	v_cvt_pk_bf16_f32 v98, v98, v99
	s_nop 0
	s_nop 0
	s_nop 0
	s_nop 0
	v_add_co_u32_e32 v96, vcc, s16, v96
	v_cvt_pk_bf16_f32 v99, v100, v101
	s_nop 0
	v_addc_co_u32_e32 v97, vcc, 0, v97, vcc
	global_store_dwordx2 v[122:123], v[104:105], off offset:1024
	global_store_dwordx2 v[96:97], v[98:99], off
	v_pk_mul_f32 v[98:99], v[108:109], v[46:47] op_sel_hi:[1,0]
	v_pk_mul_f32 v[100:101], v[112:113], v[46:47] op_sel_hi:[1,0]
	v_pk_fma_f32 v[98:99], v[4:5], v[98:99], v[12:13]
	v_pk_fma_f32 v[100:101], v[6:7], v[100:101], v[14:15]
	v_cvt_pk_bf16_f32 v98, v98, v99
	v_pk_mul_f32 v[86:87], v[86:87], v[46:47] op_sel_hi:[1,0]
	v_pk_fma_f32 v[86:87], v[16:17], v[86:87], v[24:25]
	v_cvt_pk_bf16_f32 v99, v100, v101
	v_pk_mul_f32 v[88:89], v[88:89], v[46:47] op_sel_hi:[1,0]
	v_pk_fma_f32 v[88:89], v[18:19], v[88:89], v[26:27]
	v_cvt_pk_bf16_f32 v86, v86, v87
	v_pk_mul_f32 v[80:81], v[80:81], v[46:47] op_sel_hi:[1,0]
	v_pk_fma_f32 v[80:81], v[20:21], v[80:81], v[28:29]
	v_cvt_pk_bf16_f32 v87, v88, v89
	v_pk_mul_f32 v[78:79], v[78:79], v[46:47] op_sel_hi:[1,0]
	v_pk_fma_f32 v[78:79], v[22:23], v[78:79], v[30:31]
	v_cvt_pk_bf16_f32 v80, v80, v81
	s_nop 0
	s_nop 0
	s_nop 0
	v_cvt_pk_bf16_f32 v81, v78, v79
	global_store_dwordx2 v[96:97], v[80:81], off offset:1536
	v_lshlrev_b32_e32 v79, 16, v93
	v_lshlrev_b32_e32 v78, 16, v92
	v_and_b32_e32 v81, 0xffff0000, v93
	v_and_b32_e32 v80, 0xffff0000, v92
	v_pk_add_f32 v[82:83], v[78:79], v[80:81]
	global_store_dwordx2 v[96:97], v[86:87], off offset:1024
	v_add_f32_e32 v33, v82, v83
	v_lshlrev_b32_e32 v83, 16, v91
	v_lshlrev_b32_e32 v82, 16, v90
	v_pk_add_f32 v[86:87], v[82:83], v[84:85]
	v_add_f32_e32 v66, 0, v33
	v_pk_add_f32 v[86:87], v[86:87], v[86:87] op_sel:[0,1] op_sel_hi:[1,0]
	v_pk_add_f32 v[88:89], v[64:65], v[60:61]
	v_mov_b32_e32 v87, v63
	v_pk_add_f32 v[86:87], v[66:67], v[86:87]
	global_store_dwordx2 v[96:97], v[98:99], off offset:512
	v_pk_add_f32 v[86:87], v[86:87], v[88:89]
	v_lshl_add_u64 v[42:43], v[42:43], 0, s[14:15]
	v_add_f32_e32 v33, v86, v87
	s_nop 1
	v_add_f32_dpp v33, v33, v33 quad_perm:[1,0,3,2] row_mask:0xf bank_mask:0xf bound_ctrl:1
	s_nop 1
	v_add_f32_dpp v33, v33, v33 quad_perm:[2,3,0,1] row_mask:0xf bank_mask:0xf bound_ctrl:1
	s_nop 1
	v_add_f32_dpp v33, v33, v33 row_half_mirror row_mask:0xf bank_mask:0xf bound_ctrl:1
	s_nop 1
	v_add_f32_dpp v33, v33, v33 row_mirror row_mask:0xf bank_mask:0xf bound_ctrl:1
	s_nop 0
	v_readlane_b32 s8, v33, 16
	v_readlane_b32 s9, v33, 48
	v_readlane_b32 s0, v33, 0
	v_readlane_b32 s1, v33, 32
	v_mov_b32_e32 v86, s8
	v_mov_b32_e32 v87, s9
	v_pk_add_f32 v[86:87], s[0:1], v[86:87]
	s_nop 0
	v_add_f32_e32 v33, v86, v87
	v_fmac_f32_e32 v80, 0xba800000, v33
	v_fmac_f32_e32 v81, 0xba800000, v33
	v_fmac_f32_e32 v79, 0xba800000, v33
	v_fmac_f32_e32 v78, 0xba800000, v33
	v_mov_b32_e32 v86, v79
	v_mov_b32_e32 v87, v81
	v_mov_b32_e32 v79, v80
	v_pk_mul_f32 v[88:89], v[86:87], v[86:87]
	v_pk_mul_f32 v[80:81], v[78:79], v[78:79]
	v_fmac_f32_e32 v84, 0xba800000, v33
	v_fmac_f32_e32 v85, 0xba800000, v33
	v_fmac_f32_e32 v83, 0xba800000, v33
	v_pk_mov_b32 v[90:91], v[80:81], v[88:89] op_sel:[1,0]
	v_mov_b32_e32 v81, v89
	v_fmac_f32_e32 v82, 0xba800000, v33
	v_mov_b32_e32 v88, v83
	v_mov_b32_e32 v89, v85
	v_mov_b32_e32 v83, v84
	v_pk_add_f32 v[80:81], v[90:91], v[80:81]
	v_pk_mul_f32 v[90:91], v[88:89], v[88:89]
	v_pk_mul_f32 v[84:85], v[82:83], v[82:83]
	v_fmac_f32_e32 v68, 0xba800000, v33
	v_pk_mov_b32 v[92:93], v[84:85], v[90:91] op_sel:[1,0]
	v_mov_b32_e32 v85, v91
	v_fmac_f32_e32 v69, 0xba800000, v33
	v_fmac_f32_e32 v70, 0xba800000, v33
	v_mul_f32_e32 v46, v68, v68
	v_pk_add_f32 v[84:85], v[92:93], v[84:85]
	v_fmac_f32_e32 v71, 0xba800000, v33
	v_pk_fma_f32 v[90:91], v[68:69], v[68:69], v[46:47] op_sel_hi:[1,1,0]
	v_mul_f32_e32 v46, v70, v70
	v_pk_add_f32 v[80:81], v[80:81], v[80:81] op_sel_hi:[0,1]
	v_pk_add_f32 v[84:85], v[84:85], v[84:85] op_sel_hi:[0,1]
	v_pk_fma_f32 v[92:93], v[70:71], v[70:71], v[46:47] op_sel_hi:[1,1,0]
; DI float wave_sum(float v) { v = row16_sum(v); return (rdlane(v, 0) + rdlane(v, 16)) + (rdlane(v, 32) + rdlane(v, 48)); }
; DI void phase_ln(const bf16_t* vin, float* xf, bf16_t* xb, const float* g, const float* b, bool write_f32) {
;     ...
;         for (int k = 0; k < R; ++k) {
;             float s = 0.f;
; #pragma unroll
;             for (int i = 0; i < 4; ++i) s += (v[k][i][0] + v[k][i][1]) + (v[k][i][2] + v[k][i][3]);
;             const float mean = wave_sum(s) * (1.0f / 1024.0f);
;             float q = 0.f;
; #pragma unroll
;             for (int i = 0; i < 4; ++i) { const f32x4 d = v[k][i] - mean; q += (d[0] * d[0] + d[1] * d[1]) + (d[2] * d[2] + d[3] * d[3]); }
;             const float rstd = rsqrtf(wave_sum(q) * (1.0f / 1024.0f) + 1e-5f);
	v_fmac_f32_e32 v61, 0xba800000, v33
	v_fmac_f32_e32 v65, 0xba800000, v33
	v_fmac_f32_e32 v63, 0xba800000, v33
	v_fmac_f32_e32 v67, 0xba800000, v33
	v_mul_f32_e32 v90, v67, v67
	v_mul_f32_e32 v92, v63, v63
	v_mul_f32_e32 v80, v65, v65
	v_mul_f32_e32 v84, v61, v61
	v_pk_add_f32 v[90:91], v[90:91], v[92:93]
	v_pk_add_f32 v[80:81], v[80:81], v[84:85]
	v_lshlrev_b32_e32 v85, 16, v77
	v_pk_add_f32 v[80:81], v[90:91], v[80:81]
	v_lshlrev_b32_e32 v84, 16, v76
	v_add_f32_e32 v33, v80, v81
	v_and_b32_e32 v77, 0xffff0000, v77
	v_and_b32_e32 v76, 0xffff0000, v76
	v_add_f32_dpp v33, v33, v33 quad_perm:[1,0,3,2] row_mask:0xf bank_mask:0xf bound_ctrl:1
	v_pk_add_f32 v[90:91], v[84:85], v[76:77]
	v_add_f32_e32 v46, v56, v57
	v_add_f32_dpp v33, v33, v33 quad_perm:[2,3,0,1] row_mask:0xf bank_mask:0xf bound_ctrl:1
	v_pk_add_f32 v[96:97], v[50:51], v[46:47]
	v_mov_b32_e32 v62, v67
	v_add_f32_dpp v33, v33, v33 row_half_mirror row_mask:0xf bank_mask:0xf bound_ctrl:1
	v_mov_b32_e32 v60, v65
	s_nop 0
	v_add_f32_dpp v33, v33, v33 row_mirror row_mask:0xf bank_mask:0xf bound_ctrl:1
	s_nop 0
	v_readlane_b32 s0, v33, 0
	v_readlane_b32 s8, v33, 16
	v_readlane_b32 s1, v33, 32
	v_readlane_b32 s9, v33, 48
	v_add_f32_e32 v33, v90, v91
	v_lshlrev_b32_e32 v91, 16, v75
	v_lshlrev_b32_e32 v90, 16, v74
	v_and_b32_e32 v75, 0xffff0000, v75
	v_and_b32_e32 v74, 0xffff0000, v74
	v_pk_add_f32 v[92:93], v[90:91], v[74:75]
	v_add_f32_e32 v52, 0, v33
	v_pk_add_f32 v[92:93], v[92:93], v[92:93] op_sel:[0,1] op_sel_hi:[1,0]
	v_mov_b32_e32 v80, s8
	v_mov_b32_e32 v93, v49
	v_pk_add_f32 v[92:93], v[52:53], v[92:93]
	v_mov_b32_e32 v81, s9
	v_pk_add_f32 v[92:93], v[92:93], v[96:97]
	v_pk_add_f32 v[80:81], s[0:1], v[80:81]
	v_add_f32_e32 v33, v92, v93
	s_nop 1
	v_add_f32_dpp v33, v33, v33 quad_perm:[1,0,3,2] row_mask:0xf bank_mask:0xf bound_ctrl:1
	s_nop 1
	v_add_f32_dpp v33, v33, v33 quad_perm:[2,3,0,1] row_mask:0xf bank_mask:0xf bound_ctrl:1
	s_nop 1
	v_add_f32_dpp v33, v33, v33 row_half_mirror row_mask:0xf bank_mask:0xf bound_ctrl:1
	s_nop 1
	v_add_f32_dpp v33, v33, v33 row_mirror row_mask:0xf bank_mask:0xf bound_ctrl:1
	s_nop 0
	v_readlane_b32 s8, v33, 16
	v_readlane_b32 s9, v33, 48
	v_readlane_b32 s0, v33, 0
	v_readlane_b32 s1, v33, 32
	v_mov_b32_e32 v92, s8
	v_mov_b32_e32 v93, s9
	v_pk_add_f32 v[92:93], s[0:1], v[92:93]
	s_nop 0
	v_add_f32_e32 v33, v92, v93
	v_fmac_f32_e32 v76, 0xba800000, v33
	v_fmac_f32_e32 v77, 0xba800000, v33
	v_fmac_f32_e32 v85, 0xba800000, v33
	v_fmac_f32_e32 v84, 0xba800000, v33
	v_mov_b32_e32 v92, v85
	v_mov_b32_e32 v93, v77
	v_mov_b32_e32 v85, v76
	v_pk_mul_f32 v[96:97], v[92:93], v[92:93]
	v_pk_mul_f32 v[76:77], v[84:85], v[84:85]
	v_fmac_f32_e32 v74, 0xba800000, v33
	v_fmac_f32_e32 v75, 0xba800000, v33
	v_fmac_f32_e32 v91, 0xba800000, v33
	v_pk_mov_b32 v[98:99], v[76:77], v[96:97] op_sel:[1,0]
	v_mov_b32_e32 v77, v97
	v_fmac_f32_e32 v90, 0xba800000, v33
	v_mov_b32_e32 v96, v91
	v_mov_b32_e32 v97, v75
	v_mov_b32_e32 v91, v74
	v_pk_add_f32 v[76:77], v[98:99], v[76:77]
	v_pk_mul_f32 v[98:99], v[96:97], v[96:97]
	v_pk_mul_f32 v[74:75], v[90:91], v[90:91]
	v_fmac_f32_e32 v54, 0xba800000, v33
	v_pk_mov_b32 v[100:101], v[74:75], v[98:99] op_sel:[1,0]
	v_mov_b32_e32 v75, v99
	v_fmac_f32_e32 v55, 0xba800000, v33
	v_fmac_f32_e32 v56, 0xba800000, v33
	v_mul_f32_e32 v46, v54, v54
	v_pk_add_f32 v[74:75], v[100:101], v[74:75]
	v_fmac_f32_e32 v57, 0xba800000, v33
	v_pk_fma_f32 v[98:99], v[54:55], v[54:55], v[46:47] op_sel_hi:[1,1,0]
	v_mul_f32_e32 v46, v56, v56
	v_pk_add_f32 v[76:77], v[76:77], v[76:77] op_sel_hi:[0,1]
	v_pk_add_f32 v[74:75], v[74:75], v[74:75] op_sel_hi:[0,1]
	v_pk_fma_f32 v[100:101], v[56:57], v[56:57], v[46:47] op_sel_hi:[1,1,0]
	v_fmac_f32_e32 v47, 0xba800000, v33
	v_fmac_f32_e32 v51, 0xba800000, v33
	v_fmac_f32_e32 v49, 0xba800000, v33
	v_fmac_f32_e32 v53, 0xba800000, v33
	v_mul_f32_e32 v98, v53, v53
	v_mul_f32_e32 v100, v49, v49
	v_mul_f32_e32 v76, v51, v51
	v_mul_f32_e32 v74, v47, v47
	v_pk_add_f32 v[98:99], v[98:99], v[100:101]
	v_pk_add_f32 v[74:75], v[76:77], v[74:75]
	v_mov_b32_e32 v77, v80
	v_pk_add_f32 v[74:75], v[98:99], v[74:75]
	s_nop 0
	v_add_f32_e32 v33, v74, v75
	s_nop 1
	v_add_f32_dpp v33, v33, v33 quad_perm:[1,0,3,2] row_mask:0xf bank_mask:0xf bound_ctrl:1
; DI unsigned pk2(float lo, float hi) { return f2bf(lo) | (f2bf(hi) << 16); }
; DI float wave_sum(float v) { v = row16_sum(v); return (rdlane(v, 0) + rdlane(v, 16)) + (rdlane(v, 32) + rdlane(v, 48)); }
; DI void phase_ln(const bf16_t* vin, float* xf, bf16_t* xb, const float* g, const float* b, bool write_f32) {
;     ...
;             const float rstd = rsqrtf(wave_sum(q) * (1.0f / 1024.0f) + 1e-5f);
;             float* row = xf + (size_t)(r0 + k * nw) * D_;
;             bf16_t* rb = xb + (size_t)(r0 + k * nw) * D_;
; #pragma unroll
;             for (int i = 0; i < 4; ++i) {
;                 const f32x4 o = (v[k][i] - mean) * rstd * gv[i] + bv[i];
;                 if (write_f32) *(f32x4*)(row + i * 256 + lane * 4) = o;
;                 u32x2 w; w.x = pk2(o[0], o[1]); w.y = pk2(o[2], o[3]);
;                 *(u32x2*)(rb + i * 256 + lane * 4) = w;
	s_nop 1
	v_add_f32_dpp v33, v33, v33 quad_perm:[2,3,0,1] row_mask:0xf bank_mask:0xf bound_ctrl:1
	s_nop 1
	v_add_f32_dpp v33, v33, v33 row_half_mirror row_mask:0xf bank_mask:0xf bound_ctrl:1
	s_nop 1
	v_add_f32_dpp v33, v33, v33 row_mirror row_mask:0xf bank_mask:0xf bound_ctrl:1
	s_nop 0
	v_readlane_b32 s8, v33, 16
	v_readlane_b32 s9, v33, 48
	v_readlane_b32 s0, v33, 0
	v_readlane_b32 s1, v33, 32
	v_mov_b32_e32 v74, s8
	v_mov_b32_e32 v75, s9
	v_pk_add_f32 v[74:75], s[0:1], v[74:75]
	s_nop 0
	v_mov_b32_e32 v76, v74
	v_mov_b32_e32 v80, v75
	v_pk_add_f32 v[74:75], v[76:77], v[80:81]
	s_nop 0
	v_pk_fma_f32 v[74:75], v[74:75], s[18:19], v[94:95] op_sel_hi:[1,0,0]
	s_nop 0
	v_mul_f32_e32 v33, 0x4b800000, v75
	v_cmp_gt_f32_e64 s[0:1], s44, v75
	v_cmp_gt_f32_e32 vcc, s44, v74
	s_nop 0
	v_cndmask_b32_e64 v33, v75, v33, s[0:1]
	v_rsq_f32_e32 v33, v33
	s_nop 0
	v_mul_f32_e32 v46, 0x45800000, v33
	v_cndmask_b32_e64 v46, v33, v46, s[0:1]
	v_pk_mul_f32 v[76:77], v[78:79], v[46:47] op_sel_hi:[1,0]
	v_pk_mul_f32 v[78:79], v[86:87], v[46:47] op_sel_hi:[1,0]
	v_pk_fma_f32 v[76:77], v[0:1], v[76:77], v[8:9]
	v_pk_fma_f32 v[78:79], v[2:3], v[78:79], v[10:11]
	v_cvt_pk_bf16_f32 v76, v76, v77
	s_nop 0
	s_nop 0
	s_nop 0
	v_cvt_pk_bf16_f32 v77, v78, v79
	global_store_dwordx2 v[72:73], v[76:77], off
	v_pk_mul_f32 v[76:77], v[82:83], v[46:47] op_sel_hi:[1,0]
	v_pk_mul_f32 v[78:79], v[88:89], v[46:47] op_sel_hi:[1,0]
	v_pk_fma_f32 v[76:77], v[4:5], v[76:77], v[12:13]
	v_pk_fma_f32 v[78:79], v[6:7], v[78:79], v[14:15]
	v_cvt_pk_bf16_f32 v76, v76, v77
	v_pk_mul_f32 v[68:69], v[68:69], v[46:47] op_sel_hi:[1,0]
	v_pk_fma_f32 v[68:69], v[16:17], v[68:69], v[24:25]
	v_cvt_pk_bf16_f32 v77, v78, v79
	v_pk_mul_f32 v[70:71], v[70:71], v[46:47] op_sel_hi:[1,0]
	v_pk_fma_f32 v[70:71], v[18:19], v[70:71], v[26:27]
	v_cvt_pk_bf16_f32 v68, v68, v69
	v_pk_mul_f32 v[62:63], v[62:63], v[46:47] op_sel_hi:[1,0]
	v_pk_fma_f32 v[62:63], v[20:21], v[62:63], v[28:29]
	v_cvt_pk_bf16_f32 v69, v70, v71
	v_pk_mul_f32 v[60:61], v[60:61], v[46:47] op_sel_hi:[1,0]
	v_pk_fma_f32 v[60:61], v[22:23], v[60:61], v[30:31]
	v_cvt_pk_bf16_f32 v62, v62, v63
	s_nop 0
	s_nop 0
	v_cvt_pk_bf16_f32 v63, v60, v61
	v_mul_f32_e32 v33, 0x4b800000, v74
	v_cndmask_b32_e32 v33, v74, v33, vcc
	v_rsq_f32_e32 v33, v33
	global_store_dwordx2 v[72:73], v[62:63], off offset:1536
	v_mov_b32_e32 v48, v53
	s_mov_b32 s0, 0xffff
	v_mul_f32_e32 v46, 0x45800000, v33
	v_cndmask_b32_e32 v50, v33, v46, vcc
	v_pk_mul_f32 v[60:61], v[84:85], v[50:51] op_sel_hi:[1,0]
	v_pk_mul_f32 v[62:63], v[92:93], v[50:51] op_sel_hi:[1,0]
	v_pk_fma_f32 v[60:61], v[0:1], v[60:61], v[8:9]
	v_pk_fma_f32 v[62:63], v[2:3], v[62:63], v[10:11]
	v_cvt_pk_bf16_f32 v60, v60, v61
	s_nop 0
	s_nop 0
	s_nop 0
	v_cvt_pk_bf16_f32 v61, v62, v63
	global_store_dwordx2 v[58:59], v[60:61], off
	v_pk_mul_f32 v[60:61], v[90:91], v[50:51] op_sel_hi:[1,0]
	v_pk_mul_f32 v[62:63], v[96:97], v[50:51] op_sel_hi:[1,0]
	v_pk_fma_f32 v[60:61], v[4:5], v[60:61], v[12:13]
	v_pk_fma_f32 v[62:63], v[6:7], v[62:63], v[14:15]
	v_cvt_pk_bf16_f32 v60, v60, v61
	v_pk_mul_f32 v[54:55], v[54:55], v[50:51] op_sel_hi:[1,0]
	v_pk_fma_f32 v[54:55], v[16:17], v[54:55], v[24:25]
	v_cvt_pk_bf16_f32 v61, v62, v63
	v_pk_mul_f32 v[56:57], v[56:57], v[50:51] op_sel_hi:[1,0]
	v_pk_fma_f32 v[56:57], v[18:19], v[56:57], v[26:27]
	v_cvt_pk_bf16_f32 v54, v54, v55
	v_pk_mul_f32 v[48:49], v[48:49], v[50:51] op_sel_hi:[1,0]
	v_pk_fma_f32 v[48:49], v[20:21], v[48:49], v[28:29]
	v_cvt_pk_bf16_f32 v55, v56, v57
	v_mov_b32_e32 v46, v51
	v_pk_mul_f32 v[46:47], v[46:47], v[50:51] op_sel_hi:[1,0]
	v_pk_fma_f32 v[46:47], v[22:23], v[46:47], v[30:31]
	v_cvt_pk_bf16_f32 v48, v48, v49
	v_cvt_pk_bf16_f32 v33, v46, v46
	s_nop 0
	v_lshrrev_b32_e32 v33, 16, v33
	v_cvt_pk_bf16_f32 v46, v47, v47
	v_cmp_lt_i32_e32 vcc, s0, v32
	v_and_or_b32 v49, v46, s39, v33
	s_or_b64 s[6:7], vcc, s[6:7]
	global_store_dwordx2 v[72:73], v[76:77], off offset:512
	global_store_dwordx2 v[72:73], v[68:69], off offset:1024
	global_store_dwordx2 v[58:59], v[60:61], off offset:512
	global_store_dwordx2 v[58:59], v[54:55], off offset:1024
	global_store_dwordx2 v[58:59], v[48:49], off offset:1536
	s_andn2_b64 exec, exec, s[6:7]
	s_cbranch_execnz .LBB0_568
